# group barriers also at in-proj->MIX1 (first workgroup of a group additionally waits for the previous group: causal history rows)
# speedup vs baseline: 1.0810x; 1.0041x over previous
.LBB0_603:
	s_sub_i32 s3, s68, 1
	s_lshl_b32 s16, 1, s3
	s_and_b32 s16, s16, 0x19b2
	s_cmp_eq_u32 s16, 0
	s_cbranch_scc1 .Lmy_xbA
	v_readlane_b32 s18, v255, 24
	s_cmp_lg_u32 s18, 0
	s_cbranch_scc1 .Lmy_xbG_known
	s_add_u32 s16, s74, 0x3600
	s_addc_u32 s17, s75, 0
	global_load_dword v4, v163, s[16:17] sc1
	global_load_dword v5, v163, s[16:17] offset:64 sc1
	global_load_dword v6, v163, s[16:17] offset:128 sc1
	global_load_dword v7, v163, s[16:17] offset:192 sc1
	global_load_dword v8, v163, s[16:17] offset:256 sc1
	global_load_dword v9, v163, s[16:17] offset:320 sc1
	global_load_dword v10, v163, s[16:17] offset:384 sc1
	global_load_dword v11, v163, s[16:17] offset:448 sc1
	s_waitcnt vmcnt(0)
	v_add_u32_e32 v12, -1, v4
	v_add_u32_e32 v13, -1, v5
	v_add_u32_e32 v14, -1, v6
	v_add_u32_e32 v15, -1, v7
	v_add_u32_e32 v16, -1, v8
	v_add_u32_e32 v17, -1, v9
	v_add_u32_e32 v18, -1, v10
	v_add_u32_e32 v19, -1, v11
	v_and_b32_e32 v12, v12, v4
	v_and_b32_e32 v13, v13, v5
	v_and_b32_e32 v14, v14, v6
	v_and_b32_e32 v15, v15, v7
	v_and_b32_e32 v16, v16, v8
	v_and_b32_e32 v17, v17, v9
	v_and_b32_e32 v18, v18, v10
	v_and_b32_e32 v19, v19, v11
	v_or3_b32 v12, v12, v13, v14
	v_or3_b32 v15, v15, v16, v17
	v_or3_b32 v12, v12, v15, v18
	v_or_b32_e32 v12, v12, v19
	v_min_u32_e32 v4, v4, v5
	v_min_u32_e32 v6, v6, v7
	v_min_u32_e32 v8, v8, v9
	v_min_u32_e32 v10, v10, v11
	v_min_u32_e32 v4, v4, v6
	v_min_u32_e32 v8, v8, v10
	v_min_u32_e32 v4, v4, v8
	v_readfirstlane_b32 s16, v12
	v_readfirstlane_b32 s17, v4
	s_cmp_eq_u32 s16, 0
	s_cselect_b32 s18, 2, 1
	s_cmp_eq_u32 s17, 0
	s_cselect_b32 s18, 1, s18
	s_nop 3
	v_writelane_b32 v255, s18, 24

.Lmy_xbG_own:
	s_sub_i32 s3, s68, 1
	s_lshl_b32 s18, 1, s3
	s_and_b32 s18, s18, 0x102
	s_cmp_eq_u32 s18, 0
	s_cbranch_scc1 .LBB0_10
	s_lshr_b32 s18, s2, 3
	s_cmp_lg_u32 s18, 0
	s_cbranch_scc1 .LBB0_10
	s_add_i32 s3, s2, 7
	s_and_b32 s3, s3, 7
	s_lshl_b32 s3, s3, 8
	s_add_u32 s16, s74, s3
	s_addc_u32 s17, s75, 0
	s_add_u32 s16, s16, 0x2400
	s_addc_u32 s17, s17, 0
	s_mov_b32 s3, 0
